# static s_setprio 1 for waves 4-7 also in the retention scan phase
# baseline (speedup 1.0000x reference)
; #define PG8_WAIT_V(n) asm volatile("s_waitcnt vmcnt(" #n ")" ::: "memory")
; #define PG8_BAR __builtin_amdgcn_s_barrier()
; DI void xcd_barrier(const XcdBarrier& b) {
;     asm volatile("s_waitcnt vmcnt(0)" ::: "memory");
;     __syncthreads();
;     if (threadIdx.x == 0) {
;         unsigned* bar = b.bar;
;         __builtin_amdgcn_s_waitcnt(0);
;         unsigned nloc = b.st[0], nx = b.st[1];
;         if (nloc == 0u) { xcd_barrier_complete(bar, b.x, nloc, nx); b.st[0] = nloc; b.st[1] = nx; }
; template <class Epi, class Sched>
; __device__ __forceinline__ void gemm_phase(PG8_LAS unsigned char* lds, const Gemm g, const Sched& S, const Epi& E) {
;     ...
;     PG8_WAIT_V(0);
;     if (wr == 0) PG8_BAR;
;     PG8_BAR;
.LBB0_245:
	s_or_b64 exec, exec, s[0:1]
	v_readlane_b32 s4, v254, 8
	v_readlane_b32 s5, v254, 9
	s_mov_b64 s[0:1], -1
	s_and_b64 vcc, exec, s[4:5]
	s_waitcnt lgkmcnt(0)
	s_barrier
	v_readfirstlane_b32 s100, v252
	s_nop 3
	s_lshr_b32 s100, s100, 6
	s_cmp_ge_u32 s100, 4
	s_cbranch_scc0 .Lscan_prio_done
	s_setprio 1
.Lscan_prio_done:
	s_cbranch_vccz .LBB0_299
	s_getreg_b32 s4, hwreg(HW_REG_XCC_ID, 0, 4)
	s_waitcnt vmcnt(0)
	s_barrier
	s_mov_b64 s[0:1], exec
	v_readlane_b32 s6, v253, 5
	v_readlane_b32 s7, v253, 6
	s_and_b64 s[6:7], s[0:1], s[6:7]
	s_mov_b64 exec, s[6:7]
	s_cbranch_execz .LBB0_298
	v_readlane_b32 s5, v255, 40
	s_waitcnt vmcnt(0) expcnt(0) lgkmcnt(0)
	s_and_b32 s10, s4, 15
	v_mov_b32_e32 v0, s5
	ds_read_b32 v2, v0
	v_readlane_b32 s5, v255, 41
	s_waitcnt lgkmcnt(0)
	v_cmp_ne_u32_e32 vcc, 0, v2
	v_mov_b32_e32 v0, s5
	ds_read_b32 v0, v0
	s_cbranch_vccnz .LBB0_262
	s_mov_b32 s11, 1
	s_branch .LBB0_250
